# v32 + sg items: four groups of a chunk on one XCC, and the first item touches the next item's v/u rows (one dword per cache line) so the second item's loads hit L2
# baseline (speedup 1.0000x reference)
; __device__ __forceinline__ void unpack8(const u32x4& w, f32x4& v0, f32x4& v1) { v0[0] = bflo(w.x); v0[1] = bfhi(w.x); v0[2] = bflo(w.y); v0[3] = bfhi(w.y); v1[0] = bflo(w.z); v1[1] = bfhi(w.z); v1[2] = bflo(w.w); v1[3] = bfhi(w.w); }
; __device__ __forceinline__ void sg_item(const Bufs& B, int l, int s, int it, unsigned char* shm) {
;     ...
;     const int ch = it >> 2, g = it & 3, m0 = ch * 128;
;     bf16_t* Wm = (bf16_t*)shm;
;     bf16_t* VnT = (bf16_t*)(shm + 34816);
;     bf16_t* uS = (bf16_t*)(shm + 69632);
;     const int t = tid >> 2, part = tid & 3, cl0 = part * 32, cg0 = g * 128 + cl0;
;     u32x4 sv[16], vq[4], uv[4]; f32x4 wv[8];
;     {
;         const u32x4* vp = (const u32x4*)(B.bufC + (size_t)(m0 + t) * 1024 + 512 + part * 128);
; #pragma unroll
;         for (int i = 0; i < 16; ++i) sv[i] = vp[i];
;         const u32x4* vqp = (const u32x4*)(B.bufC + (size_t)(m0 + t) * 1024 + 512 + cg0);
; #pragma unroll
;         for (int i = 0; i < 4; ++i) vq[i] = vqp[i];
;         const float* sw = IN(19) + (size_t)(l * 4 + g) * 16384;
; #pragma unroll
;         for (int i = 0; i < 8; ++i) wv[i] = *(const f32x4*)(sw + (tid + 512 * i) * 4);
;     }
;     __syncthreads();
;     {
;         float sum = 0.f, sq = 0.f;
; #pragma unroll
;         for (int i = 0; i < 16; ++i) { f32x4 a, bb; unpack8(sv[i], a, bb);
;             sum += (a[0] + a[1]) + (a[2] + a[3]) + (bb[0] + bb[1]) + (bb[2] + bb[3]);
;             sq += a[0] * a[0] + a[1] * a[1] + a[2] * a[2] + a[3] * a[3] + bb[0] * bb[0] + bb[1] * bb[1] + bb[2] * bb[2] + bb[3] * bb[3]; }
.LBB0_547:
	v_mov_b32_e32 v114, v179
	s_lshl_b32 s2, s27, 5
	s_and_b32 s38, s2, 0xffffff80
	v_ashrrev_i32_e32 v116, 2, v114
	v_add_u32_e32 v0, s38, v116
	v_ashrrev_i32_e32 v1, 31, v0
	v_and_b32_e32 v115, 3, v114
	v_lshlrev_b64 v[0:1], 11, v[0:1]
	v_lshl_add_u64 v[0:1], s[16:17], 0, v[0:1]
	v_lshlrev_b32_e32 v176, 8, v115
	v_lshl_add_u64 v[2:3], v[0:1], 0, v[176:177]
	s_cmpk_lt_i32 s27, 0x100
	s_cbranch_scc0 sg_warm_skip
	s_mov_b64 s[2:3], 0x1000000
	v_lshl_add_u64 v[140:141], v[2:3], 0, s[2:3]
	global_load_dword v146, v[140:141], off offset:1024
	global_load_dword v147, v[140:141], off offset:1152
	s_and_b32 s21, s27, 3
	s_lshl_b32 s21, s21, 8
	s_add_u32 s2, s2, s21
	v_lshlrev_b32_e32 v144, 7, v115
	v_mov_b32_e32 v145, 0
	v_lshl_add_u64 v[142:143], v[0:1], 0, s[2:3]
	v_lshl_add_u64 v[142:143], v[142:143], 0, v[144:145]
	global_load_dword v148, v[142:143], off
sg_warm_skip:
	global_load_dwordx4 v[96:99], v[2:3], off offset:1072
	global_load_dwordx4 v[100:103], v[2:3], off offset:1056
	global_load_dwordx4 v[104:107], v[2:3], off offset:1040
	global_load_dwordx4 v[108:111], v[2:3], off offset:1024
	global_load_dwordx4 v[80:83], v[2:3], off offset:1136
	global_load_dwordx4 v[84:87], v[2:3], off offset:1120
	global_load_dwordx4 v[88:91], v[2:3], off offset:1104
	global_load_dwordx4 v[92:95], v[2:3], off offset:1088
	global_load_dwordx4 v[64:67], v[2:3], off offset:1200
	global_load_dwordx4 v[68:71], v[2:3], off offset:1184
	global_load_dwordx4 v[72:75], v[2:3], off offset:1168
	global_load_dwordx4 v[76:79], v[2:3], off offset:1152
	global_load_dwordx4 v[48:51], v[2:3], off offset:1264
	global_load_dwordx4 v[52:55], v[2:3], off offset:1248
	global_load_dwordx4 v[56:59], v[2:3], off offset:1232
	global_load_dwordx4 v[60:63], v[2:3], off offset:1216
	s_and_b32 s20, s27, 3
	s_lshl_b32 s36, s20, 7
	v_lshl_or_b32 v117, v115, 5, s36
	v_lshlrev_b32_e32 v176, 1, v117
	s_waitcnt vmcnt(31)
	v_lshl_add_u64 v[4:5], v[0:1], 0, v[176:177]
	s_or_b32 s30, s20, s29
	global_load_dwordx4 v[0:3], v[4:5], off offset:1072
	global_load_dwordx4 v[36:39], v[4:5], off offset:1056
	global_load_dwordx4 v[40:43], v[4:5], off offset:1040
	global_load_dwordx4 v[44:47], v[4:5], off offset:1024
	s_load_dwordx2 s[2:3], s[0:1], 0x98
	s_waitcnt lgkmcnt(0)
	s_lshl_b32 s21, s30, 16
	s_add_u32 s2, s2, s21
	v_lshlrev_b32_e32 v112, 2, v114
	s_addc_u32 s3, s3, 0
	v_ashrrev_i32_e32 v113, 31, v112
	v_lshl_add_u64 v[4:5], v[112:113], 2, s[2:3]
	v_cmp_lt_i32_e32 vcc, v206, v205
	s_waitcnt vmcnt(33)
	v_add_u32_e32 v12, 0x1000, v112
	v_ashrrev_i32_e32 v13, 31, v12
	v_lshl_add_u64 v[12:13], v[12:13], 2, s[2:3]
	global_load_dwordx4 v[8:11], v[4:5], off
	s_waitcnt vmcnt(33)
	v_add_u32_e32 v16, 0x1800, v112
	global_load_dwordx4 v[12:15], v[12:13], off
	v_add_u32_e32 v4, 0x800, v112
	s_waitcnt vmcnt(33)
	v_add_u32_e32 v20, 0x2000, v112
	s_waitcnt vmcnt(32)
	v_add_u32_e32 v24, 0x2800, v112
	s_waitcnt vmcnt(31)
	v_add_u32_e32 v28, 0x3000, v112
	s_waitcnt vmcnt(30)
	v_add_u32_e32 v32, 0x3800, v112
	v_ashrrev_i32_e32 v5, 31, v4
	v_ashrrev_i32_e32 v17, 31, v16
	v_ashrrev_i32_e32 v21, 31, v20
	v_ashrrev_i32_e32 v25, 31, v24
	v_ashrrev_i32_e32 v29, 31, v28
	v_ashrrev_i32_e32 v33, 31, v32
	v_lshl_add_u64 v[4:5], v[4:5], 2, s[2:3]
	v_lshl_add_u64 v[16:17], v[16:17], 2, s[2:3]
	v_lshl_add_u64 v[20:21], v[20:21], 2, s[2:3]
	v_lshl_add_u64 v[24:25], v[24:25], 2, s[2:3]
	v_lshl_add_u64 v[28:29], v[28:29], 2, s[2:3]
	v_lshl_add_u64 v[32:33], v[32:33], 2, s[2:3]
	s_mov_b32 s2, 0x3b000000
	global_load_dwordx4 v[4:7], v[4:5], off
	s_waitcnt vmcnt(22)
	v_and_b32_e32 v134, 0xffff0000, v97
	s_waitcnt vmcnt(21)
	v_lshlrev_b32_e32 v131, 16, v100
	s_waitcnt vmcnt(20)
	v_lshlrev_b32_e32 v127, 16, v104
	s_waitcnt vmcnt(19)
	v_lshlrev_b32_e32 v123, 16, v109
	v_lshlrev_b32_e32 v122, 16, v108
	v_and_b32_e32 v118, 0xffff0000, v108
	v_and_b32_e32 v119, 0xffff0000, v109
	v_pk_mul_f32 v[108:109], v[122:123], v[122:123]
	v_lshlrev_b32_e32 v113, 16, v110
	v_fma_f32 v108, v118, v118, v108
	v_add_f32_e32 v125, v122, v118
	v_add_f32_e32 v118, v109, v108
	v_mul_f32_e32 v122, v119, v119
	v_and_b32_e32 v110, 0xffff0000, v110
	v_lshlrev_b32_e32 v120, 16, v111
	v_and_b32_e32 v121, 0xffff0000, v111
	v_and_b32_e32 v111, 0xffff0000, v104
	v_pk_add_f32 v[118:119], v[122:123], v[118:119]
	v_mul_f32_e32 v124, v113, v113
	v_pk_add_f32 v[118:119], v[124:125], v[118:119]
	v_pk_add_f32 v[124:125], v[110:111], v[112:113] op_sel_hi:[0,1]
	v_mul_f32_e32 v122, v110, v110
	v_mov_b32_e32 v123, v125
	v_pk_add_f32 v[124:125], v[120:121], v[120:121] op_sel_hi:[0,1]
	v_pk_add_f32 v[118:119], v[122:123], v[118:119]
	v_mul_f32_e32 v122, v120, v120
	v_mov_b32_e32 v123, v125
	v_lshlrev_b32_e32 v129, 16, v105
	v_pk_add_f32 v[118:119], v[122:123], v[118:119]
	v_mov_b32_e32 v122, v127
	v_mov_b32_e32 v123, v111
	v_mul_f32_e32 v124, v111, v111
	v_pk_fma_f32 v[122:123], v[122:123], v[122:123], v[124:125] op_sel_hi:[1,1,0]
	v_mul_f32_e32 v124, v129, v129
	v_and_b32_e32 v126, 0xffff0000, v106
	v_and_b32_e32 v128, 0xffff0000, v105
	v_pk_mul_f32 v[120:121], v[120:121], v[120:121]
	v_pk_add_f32 v[122:123], v[124:125], v[122:123] op_sel_hi:[0,1]
	v_mov_b32_e32 v176, v121
	v_mov_b32_e32 v110, v126
	v_lshlrev_b32_e32 v121, 16, v106
	v_pk_fma_f32 v[122:123], v[128:129], v[128:129], v[122:123]
	s_waitcnt vmcnt(17)
; __device__ __forceinline__ void unpack8(const u32x4& w, f32x4& v0, f32x4& v1) { v0[0] = bflo(w.x); v0[1] = bfhi(w.x); v0[2] = bflo(w.y); v0[3] = bfhi(w.y); v1[0] = bflo(w.z); v1[1] = bfhi(w.z); v1[2] = bflo(w.w); v1[3] = bfhi(w.w); }
; __device__ __forceinline__ void sg_item(const Bufs& B, int l, int s, int it, unsigned char* shm) {
;     ...
;         float sum = 0.f, sq = 0.f;
; #pragma unroll
;         for (int i = 0; i < 16; ++i) { f32x4 a, bb; unpack8(sv[i], a, bb);
;             sum += (a[0] + a[1]) + (a[2] + a[3]) + (bb[0] + bb[1]) + (bb[2] + bb[3]);
;             sq += a[0] * a[0] + a[1] * a[1] + a[2] * a[2] + a[3] * a[3] + bb[0] * bb[0] + bb[1] * bb[1] + bb[2] * bb[2] + bb[3] * bb[3]; }
	v_and_b32_e32 v104, 0xffff0000, v85
	v_lshlrev_b32_e32 v105, 16, v85
	v_lshlrev_b32_e32 v85, 16, v107
	v_mul_f32_e32 v124, v121, v121
	v_mov_b32_e32 v125, v129
	v_mov_b32_e32 v123, v128
	v_pk_add_f32 v[110:111], v[126:127], v[110:111]
	v_pk_add_f32 v[118:119], v[118:119], v[176:177]
	v_and_b32_e32 v176, 0xffff0000, v107
	v_mov_b32_e32 v120, v85
	v_pk_mov_b32 v[106:107], v[84:85], v[126:127] op_sel:[1,0]
	v_pk_add_f32 v[122:123], v[124:125], v[122:123]
	v_mul_f32_e32 v124, v126, v126
	v_mov_b32_e32 v125, v111
	v_pk_add_f32 v[110:111], v[124:125], v[122:123]
	v_pk_mul_f32 v[122:123], v[120:121], v[106:107]
	v_pk_add_f32 v[106:107], v[120:121], v[106:107]
	v_pk_add_f32 v[120:121], v[176:177], v[84:85] op_sel_hi:[0,1]
	v_mov_b32_e32 v123, v107
	v_pk_add_f32 v[106:107], v[122:123], v[110:111]
	v_pk_mul_f32 v[110:111], v[176:177], v[176:177]
	v_and_b32_e32 v132, 0xffff0000, v101
	v_mov_b32_e32 v111, v121
	v_lshlrev_b32_e32 v133, 16, v101
	v_pk_add_f32 v[106:107], v[110:111], v[106:107]
	v_and_b32_e32 v101, 0xffff0000, v100
	v_pk_add_f32 v[106:107], v[118:119], v[106:107]
	v_mov_b32_e32 v118, v131
	v_mov_b32_e32 v119, v101
	v_mul_f32_e32 v120, v101, v101
	v_pk_fma_f32 v[118:119], v[118:119], v[118:119], v[120:121] op_sel_hi:[1,1,0]
	v_mul_f32_e32 v120, v133, v133
	v_pk_add_f32 v[118:119], v[120:121], v[118:119] op_sel_hi:[0,1]
	v_and_b32_e32 v100, 0xffff0000, v102
	v_lshlrev_b32_e32 v111, 16, v102
	v_pk_fma_f32 v[118:119], v[132:133], v[132:133], v[118:119]
	v_mov_b32_e32 v130, v100
	v_lshlrev_b32_e32 v85, 16, v103
	v_mul_f32_e32 v120, v111, v111
	v_mov_b32_e32 v121, v133
	v_mov_b32_e32 v119, v132
	v_and_b32_e32 v176, 0xffff0000, v103
	v_pk_mov_b32 v[102:103], v[84:85], v[100:101] op_sel:[1,0]
	v_pk_add_f32 v[118:119], v[120:121], v[118:119]
	v_pk_mul_f32 v[120:121], v[100:101], v[100:101]
	v_pk_add_f32 v[100:101], v[130:131], v[100:101]
	v_mov_b32_e32 v110, v85
	v_mov_b32_e32 v121, v101
	v_pk_add_f32 v[100:101], v[120:121], v[118:119]
	v_pk_mul_f32 v[118:119], v[110:111], v[102:103]
	v_pk_add_f32 v[102:103], v[110:111], v[102:103]
	v_lshlrev_b32_e32 v135, 16, v97
	v_mov_b32_e32 v119, v103
	v_pk_mul_f32 v[102:103], v[176:177], v[176:177]
	v_pk_add_f32 v[110:111], v[176:177], v[84:85] op_sel_hi:[0,1]
	v_lshlrev_b32_e32 v85, 16, v96
	v_and_b32_e32 v97, 0xffff0000, v96
	v_pk_add_f32 v[100:101], v[118:119], v[100:101]
	v_mov_b32_e32 v103, v111
	v_mov_b32_e32 v110, v85
	v_mov_b32_e32 v111, v97
	v_mul_f32_e32 v118, v97, v97
	v_pk_fma_f32 v[110:111], v[110:111], v[110:111], v[118:119] op_sel_hi:[1,1,0]
	v_mul_f32_e32 v118, v135, v135
	v_pk_add_f32 v[100:101], v[102:103], v[100:101]
	v_and_b32_e32 v102, 0xffff0000, v98
	v_pk_add_f32 v[110:111], v[118:119], v[110:111] op_sel_hi:[0,1]
	s_waitcnt vmcnt(16)
	v_and_b32_e32 v108, 0xffff0000, v89
	v_lshlrev_b32_e32 v109, 16, v89
	v_pk_add_f32 v[100:101], v[106:107], v[100:101]
	v_and_b32_e32 v103, 16, v96
	v_mov_b32_e32 v96, v102
	v_lshlrev_b32_e32 v107, 16, v98
	v_lshlrev_b32_e32 v89, 16, v99
	v_pk_fma_f32 v[110:111], v[134:135], v[134:135], v[110:111]
	v_and_b32_e32 v176, 0xffff0000, v99
	v_pk_mov_b32 v[98:99], v[88:89], v[102:103] op_sel:[1,0]
	v_mul_f32_e32 v118, v107, v107
	v_mov_b32_e32 v119, v135
	v_mov_b32_e32 v111, v134
	v_pk_mul_f32 v[102:103], v[102:103], v[96:97]
	v_pk_add_f32 v[96:97], v[84:85], v[96:97]
	v_mov_b32_e32 v106, v89
	v_pk_add_f32 v[110:111], v[118:119], v[110:111]
	v_mov_b32_e32 v103, v97
	v_pk_add_f32 v[96:97], v[102:103], v[110:111]
	v_pk_mul_f32 v[102:103], v[106:107], v[98:99]
	v_pk_add_f32 v[98:99], v[106:107], v[98:99]
	s_waitcnt vmcnt(15)
	v_and_b32_e32 v136, 0xffff0000, v93
	v_mov_b32_e32 v103, v99
	v_lshlrev_b32_e32 v137, 16, v93
	v_pk_add_f32 v[96:97], v[102:103], v[96:97]
	v_pk_mul_f32 v[98:99], v[176:177], v[176:177]
	v_pk_add_f32 v[102:103], v[176:177], v[88:89] op_sel_hi:[0,1]
	v_lshlrev_b32_e32 v85, 16, v92
	v_and_b32_e32 v93, 0xffff0000, v92
	v_mov_b32_e32 v99, v103
	v_mov_b32_e32 v102, v85
	v_mov_b32_e32 v103, v93
	v_mul_f32_e32 v106, v93, v93
	v_pk_fma_f32 v[102:103], v[102:103], v[102:103], v[106:107] op_sel_hi:[1,1,0]
	v_mul_f32_e32 v106, v137, v137
	v_pk_add_f32 v[96:97], v[98:99], v[96:97]
	v_and_b32_e32 v98, 0xffff0000, v94
	v_pk_add_f32 v[102:103], v[106:107], v[102:103] op_sel_hi:[0,1]
	v_pk_add_f32 v[96:97], v[100:101], v[96:97]
	v_and_b32_e32 v99, 16, v92
	v_mov_b32_e32 v92, v98
	v_lshlrev_b32_e32 v101, 16, v94
	v_lshlrev_b32_e32 v89, 16, v95
	v_pk_fma_f32 v[102:103], v[136:137], v[136:137], v[102:103]
	v_and_b32_e32 v176, 0xffff0000, v95
	v_pk_mov_b32 v[94:95], v[88:89], v[98:99] op_sel:[1,0]
	v_mul_f32_e32 v106, v101, v101
	v_mov_b32_e32 v107, v137
	v_mov_b32_e32 v103, v136
	v_pk_mul_f32 v[98:99], v[98:99], v[92:93]
	v_pk_add_f32 v[92:93], v[84:85], v[92:93]
	v_mov_b32_e32 v100, v89
	v_pk_add_f32 v[102:103], v[106:107], v[102:103]
	v_mov_b32_e32 v99, v93
	v_pk_add_f32 v[92:93], v[98:99], v[102:103]
	v_pk_mul_f32 v[98:99], v[100:101], v[94:95]
	v_pk_add_f32 v[94:95], v[100:101], v[94:95]
	v_lshlrev_b32_e32 v85, 16, v88
	v_mov_b32_e32 v99, v95
	v_pk_add_f32 v[92:93], v[98:99], v[92:93]
	v_pk_mul_f32 v[94:95], v[176:177], v[176:177]
	v_pk_add_f32 v[98:99], v[176:177], v[88:89] op_sel_hi:[0,1]
	v_mov_b32_e32 v95, v99
	v_pk_add_f32 v[92:93], v[94:95], v[92:93]
	v_and_b32_e32 v95, 16, v88
	v_and_b32_e32 v94, 0xffff0000, v90
	v_and_b32_e32 v89, 0xffff0000, v88
	v_lshlrev_b32_e32 v99, 16, v91
	v_pk_add_f32 v[92:93], v[96:97], v[92:93]
	v_lshlrev_b32_e32 v97, 16, v90
	v_and_b32_e32 v176, 0xffff0000, v91
	v_pk_mov_b32 v[90:91], v[98:99], v[94:95] op_sel:[1,0]
	v_mov_b32_e32 v100, v85
	v_mov_b32_e32 v101, v89
	v_mul_f32_e32 v98, v89, v89
; __device__ __forceinline__ void unpack8(const u32x4& w, f32x4& v0, f32x4& v1) { v0[0] = bflo(w.x); v0[1] = bfhi(w.x); v0[2] = bflo(w.y); v0[3] = bfhi(w.y); v1[0] = bflo(w.z); v1[1] = bfhi(w.z); v1[2] = bflo(w.w); v1[3] = bfhi(w.w); }
; __device__ __forceinline__ void sg_item(const Bufs& B, int l, int s, int it, unsigned char* shm) {
;     ...
;         float sum = 0.f, sq = 0.f;
; #pragma unroll
;         for (int i = 0; i < 16; ++i) { f32x4 a, bb; unpack8(sv[i], a, bb);
;             sum += (a[0] + a[1]) + (a[2] + a[3]) + (bb[0] + bb[1]) + (bb[2] + bb[3]);
;             sq += a[0] * a[0] + a[1] * a[1] + a[2] * a[2] + a[3] * a[3] + bb[0] * bb[0] + bb[1] * bb[1] + bb[2] * bb[2] + bb[3] * bb[3]; }
	v_pk_fma_f32 v[100:101], v[100:101], v[100:101], v[98:99] op_sel_hi:[1,1,0]
	v_mul_f32_e32 v98, v109, v109
	v_pk_add_f32 v[100:101], v[98:99], v[100:101] op_sel_hi:[0,1]
	v_mov_b32_e32 v88, v94
	v_pk_fma_f32 v[100:101], v[108:109], v[108:109], v[100:101]
	v_mul_f32_e32 v102, v97, v97
	v_mov_b32_e32 v103, v109
	v_mov_b32_e32 v101, v108
	v_pk_mul_f32 v[94:95], v[94:95], v[88:89]
	v_pk_add_f32 v[88:89], v[84:85], v[88:89]
	v_mov_b32_e32 v96, v99
	v_pk_add_f32 v[100:101], v[102:103], v[100:101]
	v_mov_b32_e32 v95, v89
	v_pk_add_f32 v[88:89], v[94:95], v[100:101]
	v_pk_mul_f32 v[94:95], v[96:97], v[90:91]
	v_pk_add_f32 v[90:91], v[96:97], v[90:91]
	v_lshlrev_b32_e32 v85, 16, v84
	v_mov_b32_e32 v95, v91
	v_pk_add_f32 v[88:89], v[94:95], v[88:89]
	v_pk_mul_f32 v[90:91], v[176:177], v[176:177]
	v_pk_add_f32 v[94:95], v[176:177], v[98:99] op_sel_hi:[0,1]
	v_mov_b32_e32 v91, v95
	v_pk_add_f32 v[88:89], v[90:91], v[88:89]
	v_and_b32_e32 v91, 16, v84
	v_pk_add_f32 v[88:89], v[92:93], v[88:89]
	v_and_b32_e32 v93, 0xffff0000, v84
	v_mov_b32_e32 v98, v85
	v_mov_b32_e32 v99, v93
	v_mul_f32_e32 v84, v93, v93
	v_pk_fma_f32 v[98:99], v[98:99], v[98:99], v[84:85] op_sel_hi:[1,1,0]
	v_mul_f32_e32 v84, v105, v105
	v_and_b32_e32 v90, 0xffff0000, v86
	v_pk_add_f32 v[98:99], v[84:85], v[98:99] op_sel_hi:[0,1]
	v_mov_b32_e32 v92, v90
	v_lshlrev_b32_e32 v95, 16, v86
	v_lshlrev_b32_e32 v97, 16, v87
	v_pk_fma_f32 v[98:99], v[104:105], v[104:105], v[98:99]
	v_and_b32_e32 v176, 0xffff0000, v87
	v_pk_mov_b32 v[86:87], v[96:97], v[90:91] op_sel:[1,0]
	v_mul_f32_e32 v100, v95, v95
	v_mov_b32_e32 v101, v105
	v_mov_b32_e32 v99, v104
	v_pk_mul_f32 v[90:91], v[90:91], v[92:93]
	v_pk_add_f32 v[84:85], v[84:85], v[92:93]
	v_mov_b32_e32 v94, v97
	v_pk_add_f32 v[98:99], v[100:101], v[98:99]
	v_mov_b32_e32 v91, v85
	v_pk_add_f32 v[84:85], v[90:91], v[98:99]
	v_pk_mul_f32 v[90:91], v[94:95], v[86:87]
	v_pk_add_f32 v[86:87], v[94:95], v[86:87]
	v_lshlrev_b32_e32 v93, 16, v82
	v_mov_b32_e32 v91, v87
	v_pk_add_f32 v[84:85], v[90:91], v[84:85]
	v_pk_mul_f32 v[86:87], v[176:177], v[176:177]
	v_pk_add_f32 v[90:91], v[176:177], v[96:97] op_sel_hi:[0,1]
	v_mov_b32_e32 v87, v91
	v_pk_add_f32 v[84:85], v[86:87], v[84:85]
	v_and_b32_e32 v86, 0xffff0000, v81
	v_lshlrev_b32_e32 v87, 16, v81
	v_lshlrev_b32_e32 v81, 16, v80
	v_and_b32_e32 v91, 0xffff0000, v80
	v_pk_add_f32 v[84:85], v[88:89], v[84:85]
	v_and_b32_e32 v89, 16, v80
	v_mov_b32_e32 v96, v81
	v_mov_b32_e32 v97, v91
	v_mul_f32_e32 v80, v91, v91
	v_pk_fma_f32 v[96:97], v[96:97], v[96:97], v[80:81] op_sel_hi:[1,1,0]
	v_mul_f32_e32 v80, v87, v87
	v_and_b32_e32 v88, 0xffff0000, v82
	v_pk_add_f32 v[96:97], v[80:81], v[96:97] op_sel_hi:[0,1]
	v_mov_b32_e32 v90, v88
	v_lshlrev_b32_e32 v95, 16, v83
	v_pk_fma_f32 v[96:97], v[86:87], v[86:87], v[96:97]
	v_and_b32_e32 v176, 0xffff0000, v83
	v_pk_mov_b32 v[82:83], v[94:95], v[88:89] op_sel:[1,0]
	v_mul_f32_e32 v98, v93, v93
	v_mov_b32_e32 v99, v87
	v_mov_b32_e32 v97, v86
	v_pk_mul_f32 v[88:89], v[88:89], v[90:91]
	v_pk_add_f32 v[80:81], v[80:81], v[90:91]
	v_mov_b32_e32 v92, v95
	v_pk_add_f32 v[86:87], v[98:99], v[96:97]
	v_mov_b32_e32 v89, v81
	v_pk_add_f32 v[80:81], v[88:89], v[86:87]
	v_pk_mul_f32 v[86:87], v[92:93], v[82:83]
	v_pk_add_f32 v[82:83], v[92:93], v[82:83]
	s_waitcnt vmcnt(11)
	v_and_b32_e32 v89, 0xffff0000, v76
	v_mov_b32_e32 v87, v83
	v_pk_add_f32 v[80:81], v[86:87], v[80:81]
	v_pk_mul_f32 v[82:83], v[176:177], v[176:177]
	v_pk_add_f32 v[86:87], v[176:177], v[94:95] op_sel_hi:[0,1]
	v_mov_b32_e32 v83, v87
	v_pk_add_f32 v[80:81], v[82:83], v[80:81]
	v_and_b32_e32 v82, 0xffff0000, v77
	v_lshlrev_b32_e32 v83, 16, v77
	v_lshlrev_b32_e32 v77, 16, v76
	v_and_b32_e32 v87, 16, v76
	v_mov_b32_e32 v94, v77
	v_mov_b32_e32 v95, v89
	v_mul_f32_e32 v76, v89, v89
	v_pk_fma_f32 v[94:95], v[94:95], v[94:95], v[76:77] op_sel_hi:[1,1,0]
	v_mul_f32_e32 v76, v83, v83
	v_and_b32_e32 v86, 0xffff0000, v78
	v_pk_add_f32 v[94:95], v[76:77], v[94:95] op_sel_hi:[0,1]
	v_and_b32_e32 v98, 0xffff0000, v79
	v_mov_b32_e32 v88, v86
	v_lshlrev_b32_e32 v79, 16, v79
	v_lshlrev_b32_e32 v91, 16, v78
	v_pk_fma_f32 v[94:95], v[82:83], v[82:83], v[94:95]
	v_pk_mov_b32 v[92:93], v[78:79], v[86:87] op_sel:[1,0]
	v_mul_f32_e32 v96, v91, v91
	v_mov_b32_e32 v97, v83
	v_mov_b32_e32 v95, v82
	v_pk_mul_f32 v[86:87], v[86:87], v[88:89]
	v_pk_add_f32 v[76:77], v[76:77], v[88:89]
	v_mov_b32_e32 v90, v79
	v_pk_add_f32 v[82:83], v[96:97], v[94:95]
	v_mov_b32_e32 v87, v77
	v_pk_add_f32 v[76:77], v[86:87], v[82:83]
	v_pk_mul_f32 v[82:83], v[90:91], v[92:93]
	v_pk_add_f32 v[86:87], v[90:91], v[92:93]
	v_and_b32_e32 v89, 0xffff0000, v72
	v_mov_b32_e32 v83, v87
	v_pk_add_f32 v[76:77], v[82:83], v[76:77]
	v_and_b32_e32 v82, 0xffff0000, v73
	v_lshlrev_b32_e32 v83, 16, v73
	v_lshlrev_b32_e32 v73, 16, v72
	v_and_b32_e32 v87, 16, v72
	v_and_b32_e32 v86, 0xffff0000, v74
	v_mov_b32_e32 v90, v73
	v_mov_b32_e32 v91, v89
	v_mul_f32_e32 v72, v89, v89
	v_mov_b32_e32 v88, v86
	v_pk_fma_f32 v[90:91], v[90:91], v[90:91], v[72:73] op_sel_hi:[1,1,0]
	v_mul_f32_e32 v72, v83, v83
	v_pk_add_f32 v[90:91], v[72:73], v[90:91] op_sel_hi:[0,1]
	v_pk_mul_f32 v[92:93], v[86:87], v[88:89]
	v_pk_add_f32 v[72:73], v[72:73], v[88:89]
	v_pk_fma_f32 v[90:91], v[82:83], v[82:83], v[90:91]
	v_mov_b32_e32 v93, v73
	v_lshlrev_b32_e32 v73, 16, v75
	v_lshlrev_b32_e32 v72, 16, v74
	v_pk_mul_f32 v[88:89], v[72:73], v[72:73]
	v_mov_b32_e32 v91, v82
	v_mov_b32_e32 v82, v88
	v_pk_add_f32 v[82:83], v[82:83], v[90:91]
	v_and_b32_e32 v91, 0xffff0000, v68
	v_lshlrev_b32_e32 v90, 16, v68
	v_mul_f32_e32 v68, v91, v91
	v_and_b32_e32 v94, 0xffff0000, v75
	v_pk_add_f32 v[82:83], v[92:93], v[82:83]
; __device__ __forceinline__ void unpack8(const u32x4& w, f32x4& v0, f32x4& v1) { v0[0] = bflo(w.x); v0[1] = bfhi(w.x); v0[2] = bflo(w.y); v0[3] = bfhi(w.y); v1[0] = bflo(w.z); v1[1] = bfhi(w.z); v1[2] = bflo(w.w); v1[3] = bfhi(w.w); }
; __device__ __forceinline__ void sg_item(const Bufs& B, int l, int s, int it, unsigned char* shm) {
;     ...
;         float sum = 0.f, sq = 0.f;
; #pragma unroll
;         for (int i = 0; i < 16; ++i) { f32x4 a, bb; unpack8(sv[i], a, bb);
;             sum += (a[0] + a[1]) + (a[2] + a[3]) + (bb[0] + bb[1]) + (bb[2] + bb[3]);
;             sq += a[0] * a[0] + a[1] * a[1] + a[2] * a[2] + a[3] * a[3] + bb[0] * bb[0] + bb[1] * bb[1] + bb[2] * bb[2] + bb[3] * bb[3]; }
;         sum += __shfl_xor(sum, 1); sum += __shfl_xor(sum, 2); sq += __shfl_xor(sq, 1); sq += __shfl_xor(sq, 2);
	v_pk_add_f32 v[92:93], v[90:91], v[90:91] op_sel_hi:[0,1]
	v_pk_fma_f32 v[90:91], v[90:91], v[90:91], v[68:69] op_sel_hi:[1,1,0]
	v_and_b32_e32 v68, 0xffff0000, v69
	v_lshlrev_b32_e32 v69, 16, v69
	v_add_f32_e32 v75, v73, v94
	v_pk_add_f32 v[72:73], v[72:73], v[86:87]
	v_lshlrev_b32_e32 v87, 16, v71
	v_mul_f32_e32 v86, v69, v69
	v_pk_add_f32 v[90:91], v[86:87], v[90:91] op_sel_hi:[0,1]
	v_pk_mov_b32 v[72:73], v[88:89], v[72:73] op_sel:[1,0]
	v_lshlrev_b32_e32 v88, 16, v70
	v_pk_fma_f32 v[90:91], v[68:69], v[68:69], v[90:91]
	v_mul_f32_e32 v74, v94, v94
	v_and_b32_e32 v96, 0xffff0000, v70
	v_mul_f32_e32 v94, v88, v88
	v_mov_b32_e32 v95, v69
	v_mov_b32_e32 v91, v68
	v_and_b32_e32 v97, 0xffff0000, v64
	v_add_f32_e32 v89, v88, v96
	v_pk_add_f32 v[68:69], v[94:95], v[90:91]
	v_mul_f32_e32 v92, v96, v96
	v_lshlrev_b32_e32 v94, 16, v64
	v_and_b32_e32 v96, s0, v64
	v_mov_b32_e32 v95, v97
	v_mul_f32_e32 v64, v97, v97
	v_add_f32_e32 v79, v79, v98
	v_mul_f32_e32 v78, v98, v98
	v_pk_add_f32 v[98:99], v[94:95], v[96:97] op_sel_hi:[0,1]
	v_pk_fma_f32 v[94:95], v[94:95], v[94:95], v[64:65] op_sel_hi:[1,1,0]
	v_and_b32_e32 v64, 0xffff0000, v65
	v_lshlrev_b32_e32 v65, 16, v65
	v_and_b32_e32 v70, 0xffff0000, v71
	v_lshlrev_b32_e32 v91, 16, v66
	v_and_b32_e32 v71, 0xffff0000, v66
	v_lshlrev_b32_e32 v90, 16, v67
	v_and_b32_e32 v66, 0xffff0000, v67
	v_mul_f32_e32 v86, v65, v65
	s_waitcnt vmcnt(7)
	v_lshlrev_b32_e32 v97, 16, v60
	v_and_b32_e32 v67, 0xffff0000, v60
	v_and_b32_e32 v100, 0xffff0000, v61
	v_lshlrev_b32_e32 v101, 16, v61
	v_and_b32_e32 v60, 0xffff0000, v49
	v_lshlrev_b32_e32 v61, 16, v49
	v_cndmask_b32_e32 v49, v204, v206, vcc
	v_pk_add_f32 v[80:81], v[84:85], v[80:81]
	v_pk_add_f32 v[76:77], v[78:79], v[76:77]
	v_pk_add_f32 v[72:73], v[72:73], v[82:83]
	v_pk_add_f32 v[94:95], v[86:87], v[94:95] op_sel_hi:[0,1]
	v_lshlrev_b32_e32 v86, 2, v49
	v_pk_add_f32 v[76:77], v[80:81], v[76:77]
	v_pk_add_f32 v[72:73], v[74:75], v[72:73]
	v_pk_add_f32 v[68:69], v[92:93], v[68:69]
	v_pk_add_f32 v[72:73], v[76:77], v[72:73]
	v_mul_f32_e32 v88, v87, v87
	v_pk_add_f32 v[76:77], v[70:71], v[86:87] op_sel_hi:[0,1]
	v_pk_add_f32 v[68:69], v[88:89], v[68:69]
	v_mul_f32_e32 v74, v70, v70
	v_mov_b32_e32 v75, v77
	v_pk_add_f32 v[68:69], v[74:75], v[68:69]
	v_pk_fma_f32 v[94:95], v[64:65], v[64:65], v[94:95]
	v_pk_add_f32 v[68:69], v[72:73], v[68:69]
	v_pk_mul_f32 v[72:73], v[90:91], v[90:91]
	v_mov_b32_e32 v70, v90
	v_mov_b32_e32 v72, v73
	v_mov_b32_e32 v73, v65
	v_mov_b32_e32 v95, v64
	v_cmp_lt_i32_e32 vcc, v207, v205
	v_pk_add_f32 v[64:65], v[72:73], v[94:95]
	v_pk_mul_f32 v[72:73], v[70:71], v[70:71]
	v_cndmask_b32_e32 v49, v204, v207, vcc
	v_mov_b32_e32 v98, v73
	v_pk_add_f32 v[70:71], v[90:91], v[70:71]
	v_lshlrev_b32_e32 v108, 2, v49
	v_mov_b32_e32 v49, v90
	v_pk_add_f32 v[64:65], v[98:99], v[64:65]
	v_mul_f32_e32 v72, v90, v90
	v_mov_b32_e32 v73, v71
	v_pk_add_f32 v[64:65], v[72:73], v[64:65]
	v_pk_add_f32 v[72:73], v[66:67], v[48:49] op_sel_hi:[0,1]
	v_mul_f32_e32 v70, v66, v66
	v_mov_b32_e32 v71, v73
	v_pk_add_f32 v[64:65], v[70:71], v[64:65]
	v_mov_b32_e32 v70, v97
	v_mov_b32_e32 v71, v67
	v_mul_f32_e32 v72, v67, v67
	v_pk_fma_f32 v[70:71], v[70:71], v[70:71], v[72:73] op_sel_hi:[1,1,0]
	v_mul_f32_e32 v72, v101, v101
	v_and_b32_e32 v96, 0xffff0000, v62
	v_pk_add_f32 v[70:71], v[72:73], v[70:71] op_sel_hi:[0,1]
	v_pk_add_f32 v[64:65], v[68:69], v[64:65]
	v_mov_b32_e32 v66, v96
	v_lshlrev_b32_e32 v69, 16, v62
	v_pk_fma_f32 v[70:71], v[100:101], v[100:101], v[70:71]
	v_lshlrev_b32_e32 v49, 16, v63
	v_mul_f32_e32 v72, v69, v69
	v_mov_b32_e32 v73, v101
	v_mov_b32_e32 v71, v100
	v_pk_add_f32 v[66:67], v[96:97], v[66:67]
	v_and_b32_e32 v176, 0xffff0000, v63
	v_mov_b32_e32 v68, v49
	v_pk_mov_b32 v[62:63], v[48:49], v[96:97] op_sel:[1,0]
	v_pk_add_f32 v[70:71], v[72:73], v[70:71]
	v_mul_f32_e32 v72, v96, v96
	v_mov_b32_e32 v73, v67
	v_pk_add_f32 v[66:67], v[72:73], v[70:71]
	v_pk_mul_f32 v[70:71], v[68:69], v[62:63]
	v_pk_add_f32 v[62:63], v[68:69], v[62:63]
	v_pk_add_f32 v[68:69], v[176:177], v[48:49] op_sel_hi:[0,1]
	v_mov_b32_e32 v71, v63
	v_pk_add_f32 v[62:63], v[70:71], v[66:67]
	v_pk_mul_f32 v[66:67], v[176:177], v[176:177]
	v_lshlrev_b32_e32 v103, 16, v56
	v_and_b32_e32 v104, 0xffff0000, v57
	v_lshlrev_b32_e32 v105, 16, v57
	v_mov_b32_e32 v67, v69
	v_and_b32_e32 v57, 0xffff0000, v56
	v_pk_add_f32 v[62:63], v[66:67], v[62:63]
	v_mov_b32_e32 v66, v103
	v_mov_b32_e32 v67, v57
	v_mul_f32_e32 v68, v57, v57
	v_pk_fma_f32 v[66:67], v[66:67], v[66:67], v[68:69] op_sel_hi:[1,1,0]
	v_mul_f32_e32 v68, v105, v105
	v_pk_add_f32 v[66:67], v[68:69], v[66:67] op_sel_hi:[0,1]
	v_pk_add_f32 v[62:63], v[64:65], v[62:63]
	v_and_b32_e32 v56, 0xffff0000, v58
	v_lshlrev_b32_e32 v65, 16, v58
	v_pk_fma_f32 v[66:67], v[104:105], v[104:105], v[66:67]
	v_mov_b32_e32 v102, v56
	v_lshlrev_b32_e32 v49, 16, v59
	v_mul_f32_e32 v68, v65, v65
	v_mov_b32_e32 v69, v105
	v_mov_b32_e32 v67, v104
	v_and_b32_e32 v176, 0xffff0000, v59
	v_pk_mov_b32 v[58:59], v[48:49], v[56:57] op_sel:[1,0]
	v_pk_add_f32 v[66:67], v[68:69], v[66:67]
	v_pk_mul_f32 v[68:69], v[56:57], v[56:57]
	v_pk_add_f32 v[56:57], v[102:103], v[56:57]
	v_mov_b32_e32 v64, v49
	v_mov_b32_e32 v69, v57
	v_pk_add_f32 v[56:57], v[68:69], v[66:67]
	v_pk_mul_f32 v[66:67], v[64:65], v[58:59]
	v_pk_add_f32 v[58:59], v[64:65], v[58:59]
	v_pk_add_f32 v[64:65], v[176:177], v[48:49] op_sel_hi:[0,1]
	v_mov_b32_e32 v67, v59
	v_pk_mul_f32 v[58:59], v[176:177], v[176:177]
	v_pk_add_f32 v[56:57], v[66:67], v[56:57]
	v_mov_b32_e32 v59, v65
	v_and_b32_e32 v106, 0xffff0000, v53
	v_lshlrev_b32_e32 v107, 16, v53
	v_pk_add_f32 v[56:57], v[58:59], v[56:57]
; __device__ __forceinline__ void unpack8(const u32x4& w, f32x4& v0, f32x4& v1) { v0[0] = bflo(w.x); v0[1] = bfhi(w.x); v0[2] = bflo(w.y); v0[3] = bfhi(w.y); v1[0] = bflo(w.z); v1[1] = bfhi(w.z); v1[2] = bflo(w.w); v1[3] = bfhi(w.w); }
; __device__ __forceinline__ void sg_item(const Bufs& B, int l, int s, int it, unsigned char* shm) {
;     ...
;         for (int i = 0; i < 16; ++i) { f32x4 a, bb; unpack8(sv[i], a, bb);
;             sum += (a[0] + a[1]) + (a[2] + a[3]) + (bb[0] + bb[1]) + (bb[2] + bb[3]);
;             sq += a[0] * a[0] + a[1] * a[1] + a[2] * a[2] + a[3] * a[3] + bb[0] * bb[0] + bb[1] * bb[1] + bb[2] * bb[2] + bb[3] * bb[3]; }
;         sum += __shfl_xor(sum, 1); sum += __shfl_xor(sum, 2); sq += __shfl_xor(sq, 1); sq += __shfl_xor(sq, 2);
;         const float mean = sum * (1.0f / 512.0f), var = sq * (1.0f / 512.0f) - mean * mean, rstd = rsqrtf(fmaxf(var, 0.f) + 1e-5f);
; #pragma unroll
;         for (int i = 0; i < 4; ++i) { const int idx = tid + 512 * i; uv[i] = *(const u32x4*)(B.bufC + (size_t)(m0 + (idx >> 4)) * 1024 + g * 128 + (idx & 15) * 8); }
	v_and_b32_e32 v59, 16, v52
	v_and_b32_e32 v58, 0xffff0000, v54
	v_lshlrev_b32_e32 v49, 16, v52
	v_and_b32_e32 v53, 0xffff0000, v52
	v_lshlrev_b32_e32 v65, 16, v55
	v_pk_add_f32 v[56:57], v[62:63], v[56:57]
	v_lshlrev_b32_e32 v63, 16, v54
	v_and_b32_e32 v176, 0xffff0000, v55
	v_pk_mov_b32 v[54:55], v[64:65], v[58:59] op_sel:[1,0]
	v_mov_b32_e32 v66, v49
	v_mov_b32_e32 v67, v53
	v_mul_f32_e32 v64, v53, v53
	v_pk_fma_f32 v[66:67], v[66:67], v[66:67], v[64:65] op_sel_hi:[1,1,0]
	v_mul_f32_e32 v64, v107, v107
	v_pk_add_f32 v[66:67], v[64:65], v[66:67] op_sel_hi:[0,1]
	v_mov_b32_e32 v52, v58
	v_pk_fma_f32 v[66:67], v[106:107], v[106:107], v[66:67]
	v_mul_f32_e32 v68, v63, v63
	v_mov_b32_e32 v69, v107
	v_mov_b32_e32 v67, v106
	v_pk_mul_f32 v[58:59], v[58:59], v[52:53]
	v_pk_add_f32 v[52:53], v[48:49], v[52:53]
	v_mov_b32_e32 v62, v65
	v_pk_add_f32 v[66:67], v[68:69], v[66:67]
	v_mov_b32_e32 v59, v53
	v_pk_add_f32 v[52:53], v[58:59], v[66:67]
	v_pk_mul_f32 v[58:59], v[62:63], v[54:55]
	v_pk_add_f32 v[54:55], v[62:63], v[54:55]
	v_lshlrev_b32_e32 v49, 16, v48
	v_mov_b32_e32 v59, v55
	v_pk_add_f32 v[52:53], v[58:59], v[52:53]
	v_pk_mul_f32 v[54:55], v[176:177], v[176:177]
	v_pk_add_f32 v[58:59], v[176:177], v[64:65] op_sel_hi:[0,1]
	v_mov_b32_e32 v55, v59
	v_pk_add_f32 v[52:53], v[54:55], v[52:53]
	v_and_b32_e32 v55, 16, v48
	v_pk_add_f32 v[52:53], v[56:57], v[52:53]
	v_and_b32_e32 v57, 0xffff0000, v48
	v_mov_b32_e32 v64, v49
	v_mov_b32_e32 v65, v57
	v_mul_f32_e32 v48, v57, v57
	v_pk_fma_f32 v[64:65], v[64:65], v[64:65], v[48:49] op_sel_hi:[1,1,0]
	v_mul_f32_e32 v48, v61, v61
	v_and_b32_e32 v54, 0xffff0000, v50
	v_pk_add_f32 v[64:65], v[48:49], v[64:65] op_sel_hi:[0,1]
	v_mov_b32_e32 v56, v54
	v_lshlrev_b32_e32 v59, 16, v50
	v_lshlrev_b32_e32 v63, 16, v51
	v_pk_fma_f32 v[64:65], v[60:61], v[60:61], v[64:65]
	v_and_b32_e32 v176, 0xffff0000, v51
	v_pk_mov_b32 v[50:51], v[62:63], v[54:55] op_sel:[1,0]
	v_mul_f32_e32 v66, v59, v59
	v_mov_b32_e32 v67, v61
	v_mov_b32_e32 v65, v60
	v_pk_mul_f32 v[54:55], v[54:55], v[56:57]
	v_pk_add_f32 v[48:49], v[48:49], v[56:57]
	v_mov_b32_e32 v58, v63
	v_pk_add_f32 v[60:61], v[66:67], v[64:65]
	v_mov_b32_e32 v55, v49
	v_pk_add_f32 v[48:49], v[54:55], v[60:61]
	v_pk_mul_f32 v[54:55], v[58:59], v[50:51]
	v_pk_add_f32 v[50:51], v[58:59], v[50:51]
	v_add_u32_e32 v99, 0x200, v114
	v_mov_b32_e32 v55, v51
	v_pk_add_f32 v[48:49], v[54:55], v[48:49]
	v_pk_mul_f32 v[50:51], v[176:177], v[176:177]
	v_pk_add_f32 v[54:55], v[176:177], v[62:63] op_sel_hi:[0,1]
	v_mov_b32_e32 v51, v55
	v_pk_add_f32 v[48:49], v[50:51], v[48:49]
	v_add_u32_e32 v98, 0x400, v114
	v_pk_add_f32 v[48:49], v[52:53], v[48:49]
	ds_bpermute_b32 v51, v86, v49
	ds_bpermute_b32 v50, v86, v48
	v_add_u32_e32 v97, 0x600, v114
	v_ashrrev_i32_e32 v94, 4, v99
	v_ashrrev_i32_e32 v95, 4, v98
	v_ashrrev_i32_e32 v96, 4, v97
	s_waitcnt lgkmcnt(0)
	v_pk_add_f32 v[48:49], v[48:49], v[50:51]
	ds_bpermute_b32 v51, v108, v49
	ds_bpermute_b32 v50, v108, v48
	v_add_u32_e32 v52, s38, v94
	v_add_u32_e32 v56, s38, v95
	v_add_u32_e32 v62, s38, v96
	v_ashrrev_i32_e32 v53, 31, v52
	s_waitcnt lgkmcnt(0)
	v_pk_add_f32 v[48:49], v[48:49], v[50:51]
	v_ashrrev_i32_e32 v57, 31, v56
	v_pk_mul_f32 v[92:93], v[48:49], s[2:3] op_sel_hi:[1,0]
	s_lshl_b32 s2, s20, 8
	v_fma_f32 v48, -v93, v93, v92
	v_max_f32_e32 v48, 0, v48
	v_add_f32_e32 v48, 0x3727c5ac, v48
	v_cmp_gt_f32_e32 vcc, s33, v48
	v_mul_f32_e32 v49, 0x4b800000, v48
	v_ashrrev_i32_e32 v92, 4, v114
	v_cndmask_b32_e32 v48, v48, v49, vcc
	v_rsq_f32_e32 v64, v48
	v_lshlrev_b32_e32 v48, 4, v114
	s_add_u32 s2, s16, s2
	v_and_b32_e32 v176, 0xf0, v48
	v_add_u32_e32 v48, s38, v92
	s_addc_u32 s3, s17, 0
	v_ashrrev_i32_e32 v49, 31, v48
	v_ashrrev_i32_e32 v63, 31, v62
	v_lshl_add_u64 v[60:61], s[2:3], 0, v[176:177]
	v_lshlrev_b64 v[48:49], 11, v[48:49]
	v_lshlrev_b64 v[52:53], 11, v[52:53]
	v_lshlrev_b64 v[56:57], 11, v[56:57]
	v_lshlrev_b64 v[62:63], 11, v[62:63]
	v_lshl_add_u64 v[48:49], v[60:61], 0, v[48:49]
	v_lshl_add_u64 v[52:53], v[60:61], 0, v[52:53]
	v_lshl_add_u64 v[56:57], v[60:61], 0, v[56:57]
	v_lshl_add_u64 v[60:61], v[60:61], 0, v[62:63]
	global_load_dwordx4 v[16:19], v[16:17], off
	v_mul_f32_e32 v65, 0x45800000, v64
	global_load_dwordx4 v[20:23], v[20:21], off
	v_cndmask_b32_e32 v100, v64, v65, vcc
	global_load_dwordx4 v[24:27], v[24:25], off
	s_waitcnt vmcnt(6)
	v_lshlrev_b32_e32 v64, 16, v44
	global_load_dwordx4 v[28:31], v[28:29], off
	v_lshlrev_b32_e32 v101, 2, v117
	global_load_dwordx4 v[32:35], v[32:33], off
	s_barrier
; __device__ __forceinline__ bf16_t f2bf(float f) { unsigned u = __float_as_uint(f); u += 0x7FFFu + ((u >> 16) & 1u); return (bf16_t)(u >> 16); }
; __device__ __forceinline__ void unpack8(const u32x4& w, f32x4& v0, f32x4& v1) { v0[0] = bflo(w.x); v0[1] = bfhi(w.x); v0[2] = bflo(w.y); v0[3] = bfhi(w.y); v1[0] = bflo(w.z); v1[1] = bfhi(w.z); v1[2] = bflo(w.w); v1[3] = bfhi(w.w); }
; __device__ __forceinline__ void sg_item(const Bufs& B, int l, int s, int it, unsigned char* shm) {
;     ...
;         const float* lnw = IN(17) + l * 512 + cg0; const float* lnb = IN(18) + l * 512 + cg0;
; #pragma unroll
;         for (int i = 0; i < 4; ++i) { f32x4 a, bb; unpack8(vq[i], a, bb);
; #pragma unroll
;             for (int j = 0; j < 4; ++j) {
;                 VnT[(cl0 + i * 8 + j) * 136 + t] = f2bf((a[j] - mean) * rstd * lnw[i * 8 + j] + lnb[i * 8 + j]);
;                 VnT[(cl0 + i * 8 + 4 + j) * 136 + t] = f2bf((bb[j] - mean) * rstd * lnw[i * 8 + 4 + j] + lnb[i * 8 + 4 + j]); } }
	global_load_dwordx4 v[48:51], v[48:49], off
	v_and_b32_e32 v103, 0xffff0000, v44
	global_load_dwordx4 v[52:55], v[52:53], off
	v_sub_f32_e32 v44, v64, v93
	global_load_dwordx4 v[56:59], v[56:57], off
	v_lshlrev_b32_e32 v104, 16, v45
	global_load_dwordx4 v[60:63], v[60:61], off
	s_load_dwordx2 s[2:3], s[0:1], 0x88
	s_waitcnt lgkmcnt(0)
	s_add_u32 s22, s2, s18
	s_addc_u32 s23, s3, s19
	s_load_dwordx2 s[2:3], s[0:1], 0x90
	s_waitcnt lgkmcnt(0)
	s_add_u32 s20, s2, s18
	s_addc_u32 s21, s3, s19
	v_and_b32_e32 v105, 0xffff0000, v45
	v_lshlrev_b32_e32 v106, 16, v46
	v_and_b32_e32 v107, 0xffff0000, v46
	v_lshlrev_b32_e32 v108, 16, v47
	v_and_b32_e32 v109, 0xffff0000, v47
	v_mul_f32_e32 v110, v44, v100
	global_load_dwordx4 v[44:47], v101, s[22:23] offset:48
	global_load_dwordx4 v[64:67], v101, s[22:23] offset:32
	global_load_dwordx4 v[76:79], v101, s[22:23] offset:16
	global_load_dwordx4 v[84:87], v101, s[22:23]
	global_load_dwordx4 v[68:71], v101, s[20:21] offset:48
	global_load_dwordx4 v[72:75], v101, s[20:21] offset:32
	global_load_dwordx4 v[80:83], v101, s[20:21] offset:16
	global_load_dwordx4 v[88:91], v101, s[20:21]
	v_lshlrev_b32_e32 v102, 1, v116
	s_add_i32 s39, 0, 0x11000
	s_waitcnt vmcnt(0)
	v_fma_f32 v84, v84, v110, v88
	v_bfe_u32 v88, v84, 16, 1
	v_add3_u32 v88, v84, v88, s78
	v_mul_u32_u24_e32 v84, 0x1100, v115
	v_lshlrev_b32_e32 v110, 1, v84
	v_add3_u32 v84, 0, v102, v110
	ds_write_b16_d16_hi v84, v88 offset:34816
	v_sub_f32_e32 v88, v106, v93
	v_mul_f32_e32 v88, v88, v100
	v_fma_f32 v76, v76, v88, v80
	v_bfe_u32 v80, v76, 16, 1
	v_add3_u32 v76, v76, v80, s78
	v_add3_u32 v88, 0, v110, v102
	ds_write_b16_d16_hi v88, v76 offset:35904
	v_sub_f32_e32 v76, v103, v93
	v_mul_f32_e32 v76, v76, v100
	v_fma_f32 v76, v76, v85, v89
	v_bfe_u32 v80, v76, 16, 1
	v_add3_u32 v76, v76, v80, s78
	ds_write_b16_d16_hi v84, v76 offset:35088
	v_sub_f32_e32 v76, v107, v93
	v_mul_f32_e32 v76, v76, v100
	v_fma_f32 v76, v76, v77, v81
	v_bfe_u32 v77, v76, 16, 1
	v_add3_u32 v76, v76, v77, s78
	ds_write_b16_d16_hi v88, v76 offset:36176
	v_sub_f32_e32 v76, v104, v93
	v_mul_f32_e32 v76, v76, v100
	v_fma_f32 v76, v76, v86, v90
	v_bfe_u32 v77, v76, 16, 1
	v_add3_u32 v76, v76, v77, s78
	ds_write_b16_d16_hi v84, v76 offset:35360
	v_sub_f32_e32 v76, v108, v93
	v_mul_f32_e32 v76, v76, v100
	v_fma_f32 v76, v76, v78, v82
	v_bfe_u32 v77, v76, 16, 1
	v_add3_u32 v76, v76, v77, s78
	ds_write_b16_d16_hi v88, v76 offset:36448
	v_sub_f32_e32 v76, v105, v93
	v_mul_f32_e32 v76, v76, v100
	v_fmac_f32_e32 v91, v76, v87
	v_bfe_u32 v76, v91, 16, 1
	v_add3_u32 v76, v91, v76, s78
	ds_write_b16_d16_hi v84, v76 offset:35632
	v_sub_f32_e32 v76, v109, v93
	v_mul_f32_e32 v76, v76, v100
	v_fmac_f32_e32 v83, v76, v79
	v_bfe_u32 v76, v83, 16, 1
	v_add3_u32 v76, v83, v76, s78
	ds_write_b16_d16_hi v88, v76 offset:36720
	v_lshlrev_b32_e32 v76, 16, v40
	v_sub_f32_e32 v76, v76, v93
	v_mul_f32_e32 v76, v76, v100
	v_fma_f32 v64, v76, v64, v72
	v_bfe_u32 v72, v64, 16, 1
	v_lshlrev_b32_e32 v78, 16, v42
	v_add3_u32 v64, v64, v72, s78
	ds_write_b16_d16_hi v84, v64 offset:36992
	v_sub_f32_e32 v64, v78, v93
	v_and_b32_e32 v40, 0xffff0000, v40
	v_mul_f32_e32 v64, v64, v100
	v_fma_f32 v44, v64, v44, v68
	v_sub_f32_e32 v40, v40, v93
	v_bfe_u32 v64, v44, 16, 1
	v_mul_f32_e32 v40, v40, v100
	v_add3_u32 v44, v44, v64, s78
	v_fma_f32 v40, v40, v65, v73
	ds_write_b16_d16_hi v88, v44 offset:38080
	v_bfe_u32 v44, v40, 16, 1
	v_and_b32_e32 v42, 0xffff0000, v42
	v_add3_u32 v40, v40, v44, s78
	ds_write_b16_d16_hi v84, v40 offset:37264
	v_sub_f32_e32 v40, v42, v93
	v_mul_f32_e32 v40, v40, v100
	v_fma_f32 v40, v40, v45, v69
	v_bfe_u32 v42, v40, 16, 1
	v_lshlrev_b32_e32 v77, 16, v41
	v_add3_u32 v40, v40, v42, s78
	ds_write_b16_d16_hi v88, v40 offset:38352
	v_sub_f32_e32 v40, v77, v93
	v_mul_f32_e32 v40, v40, v100
	v_fma_f32 v40, v40, v66, v74
	v_bfe_u32 v42, v40, 16, 1
	v_lshlrev_b32_e32 v79, 16, v43
	v_add3_u32 v40, v40, v42, s78
	ds_write_b16_d16_hi v84, v40 offset:37536
	v_sub_f32_e32 v40, v79, v93
	v_mul_f32_e32 v40, v40, v100
	v_fma_f32 v40, v40, v46, v70
	v_bfe_u32 v42, v40, 16, 1
	v_and_b32_e32 v41, 0xffff0000, v41
	v_add3_u32 v40, v40, v42, s78
	ds_write_b16_d16_hi v88, v40 offset:38624
	v_sub_f32_e32 v40, v41, v93
	v_mul_f32_e32 v40, v40, v100
	v_fmac_f32_e32 v75, v40, v67
	v_bfe_u32 v40, v75, 16, 1
	v_and_b32_e32 v43, 0xffff0000, v43
	v_add3_u32 v40, v75, v40, s78
	ds_write_b16_d16_hi v84, v40 offset:37808
	v_sub_f32_e32 v40, v43, v93
	v_mul_f32_e32 v40, v40, v100
	v_fmac_f32_e32 v71, v40, v47
	v_bfe_u32 v40, v71, 16, 1
	v_add3_u32 v40, v71, v40, s78
	ds_write_b16_d16_hi v88, v40 offset:38896
	v_lshlrev_b32_e32 v40, 16, v36
	v_and_b32_e32 v91, 0xffff0000, v36
	v_sub_f32_e32 v36, v40, v93
	v_lshlrev_b32_e32 v89, 16, v37
	v_and_b32_e32 v86, 0xffff0000, v37
	v_lshlrev_b32_e32 v102, 16, v38
	v_and_b32_e32 v90, 0xffff0000, v38
	v_lshlrev_b32_e32 v87, 16, v39
	v_and_b32_e32 v85, 0xffff0000, v39
	v_mul_f32_e32 v103, v36, v100
	global_load_dwordx4 v[36:39], v101, s[22:23] offset:112
	global_load_dwordx4 v[40:43], v101, s[22:23] offset:96
	global_load_dwordx4 v[44:47], v101, s[22:23] offset:80
	global_load_dwordx4 v[76:79], v101, s[22:23] offset:64
	global_load_dwordx4 v[64:67], v101, s[20:21] offset:112
	global_load_dwordx4 v[68:71], v101, s[20:21] offset:96
	global_load_dwordx4 v[72:75], v101, s[20:21] offset:80
	global_load_dwordx4 v[80:83], v101, s[20:21] offset:64
	s_waitcnt vmcnt(0)
; __device__ __forceinline__ unsigned cvt_pk_bf16(float lo, float hi) { const f32x2 v = {lo, hi}; return __builtin_bit_cast(unsigned, __builtin_convertvector(v, bf16x2_t)); }
; __device__ __forceinline__ bf16_t f2bf(float f) { unsigned u = __float_as_uint(f); u += 0x7FFFu + ((u >> 16) & 1u); return (bf16_t)(u >> 16); }
; __device__ __forceinline__ void unpack8(const u32x4& w, f32x4& v0, f32x4& v1) { v0[0] = bflo(w.x); v0[1] = bfhi(w.x); v0[2] = bflo(w.y); v0[3] = bfhi(w.y); v1[0] = bflo(w.z); v1[1] = bfhi(w.z); v1[2] = bflo(w.w); v1[3] = bfhi(w.w); }
; __device__ __forceinline__ void sg_item(const Bufs& B, int l, int s, int it, unsigned char* shm) {
;     ...
;         for (int i = 0; i < 4; ++i) { f32x4 a, bb; unpack8(vq[i], a, bb);
; #pragma unroll
;             for (int j = 0; j < 4; ++j) {
;                 VnT[(cl0 + i * 8 + j) * 136 + t] = f2bf((a[j] - mean) * rstd * lnw[i * 8 + j] + lnb[i * 8 + j]);
;                 VnT[(cl0 + i * 8 + 4 + j) * 136 + t] = f2bf((bb[j] - mean) * rstd * lnw[i * 8 + 4 + j] + lnb[i * 8 + 4 + j]); } }
; #pragma unroll
;         for (int i = 0; i < 8; ++i) { const int idx = tid + 512 * i, tt = idx >> 5, s4 = (idx & 31) * 4;
;             u32x2 w; w.x = cvt_pk_bf16(s4 <= tt ? wv[i][0] : 0.f, s4 + 1 <= tt ? wv[i][1] : 0.f); w.y = cvt_pk_bf16(s4 + 2 <= tt ? wv[i][2] : 0.f, s4 + 3 <= tt ? wv[i][3] : 0.f);
;             *(u32x2*)(Wm + tt * 136 + s4) = w; }
	v_fma_f32 v76, v103, v76, v80
	v_bfe_u32 v80, v76, 16, 1
	v_add3_u32 v76, v76, v80, s78
	ds_write_b16_d16_hi v84, v76 offset:39168
	v_sub_f32_e32 v76, v102, v93
	v_mul_f32_e32 v76, v76, v100
	v_fma_f32 v44, v76, v44, v72
	v_bfe_u32 v72, v44, 16, 1
	v_add3_u32 v44, v44, v72, s78
	ds_write_b16_d16_hi v88, v44 offset:40256
	v_sub_f32_e32 v44, v91, v93
	v_mul_f32_e32 v44, v44, v100
	v_fma_f32 v44, v44, v77, v81
	v_bfe_u32 v72, v44, 16, 1
	v_add3_u32 v44, v44, v72, s78
	ds_write_b16_d16_hi v84, v44 offset:39440
	v_sub_f32_e32 v44, v90, v93
	v_mul_f32_e32 v44, v44, v100
	v_fma_f32 v44, v44, v45, v73
	v_bfe_u32 v45, v44, 16, 1
	v_add3_u32 v44, v44, v45, s78
	ds_write_b16_d16_hi v88, v44 offset:40528
	v_sub_f32_e32 v44, v89, v93
	v_mul_f32_e32 v44, v44, v100
	v_fma_f32 v44, v44, v78, v82
	v_bfe_u32 v45, v44, 16, 1
	v_add3_u32 v44, v44, v45, s78
	ds_write_b16_d16_hi v84, v44 offset:39712
	v_sub_f32_e32 v44, v87, v93
	v_mul_f32_e32 v44, v44, v100
	v_fma_f32 v44, v44, v46, v74
	v_bfe_u32 v45, v44, 16, 1
	v_add3_u32 v44, v44, v45, s78
	ds_write_b16_d16_hi v88, v44 offset:40800
	v_sub_f32_e32 v44, v86, v93
	v_mul_f32_e32 v44, v44, v100
	v_fmac_f32_e32 v83, v44, v79
	v_bfe_u32 v44, v83, 16, 1
	v_add3_u32 v44, v83, v44, s78
	ds_write_b16_d16_hi v84, v44 offset:39984
	v_sub_f32_e32 v44, v85, v93
	v_mul_f32_e32 v44, v44, v100
	v_fmac_f32_e32 v75, v44, v47
	v_bfe_u32 v44, v75, 16, 1
	v_add3_u32 v44, v75, v44, s78
	ds_write_b16_d16_hi v88, v44 offset:41072
	v_lshlrev_b32_e32 v44, 16, v0
	v_sub_f32_e32 v44, v44, v93
	v_mul_f32_e32 v44, v44, v100
	v_fma_f32 v40, v44, v40, v68
	v_bfe_u32 v44, v40, 16, 1
	v_lshlrev_b32_e32 v46, 16, v2
	v_add3_u32 v40, v40, v44, s78
	ds_write_b16_d16_hi v84, v40 offset:41344
	v_sub_f32_e32 v40, v46, v93
	v_and_b32_e32 v0, 0xffff0000, v0
	v_mul_f32_e32 v40, v40, v100
	v_fma_f32 v36, v40, v36, v64
	v_sub_f32_e32 v0, v0, v93
	v_bfe_u32 v40, v36, 16, 1
	v_mul_f32_e32 v0, v0, v100
	v_add3_u32 v36, v36, v40, s78
	v_fma_f32 v0, v0, v41, v69
	ds_write_b16_d16_hi v88, v36 offset:42432
	v_bfe_u32 v36, v0, 16, 1
	v_and_b32_e32 v2, 0xffff0000, v2
	v_add3_u32 v0, v0, v36, s78
	ds_write_b16_d16_hi v84, v0 offset:41616
	v_sub_f32_e32 v0, v2, v93
	v_mul_f32_e32 v0, v0, v100
	v_fma_f32 v0, v0, v37, v65
	v_bfe_u32 v2, v0, 16, 1
	v_lshlrev_b32_e32 v45, 16, v1
	v_add3_u32 v0, v0, v2, s78
	ds_write_b16_d16_hi v88, v0 offset:42704
	v_sub_f32_e32 v0, v45, v93
	v_mul_f32_e32 v0, v0, v100
	v_fma_f32 v0, v0, v42, v70
	v_bfe_u32 v2, v0, 16, 1
	v_lshlrev_b32_e32 v47, 16, v3
	v_add3_u32 v0, v0, v2, s78
	ds_write_b16_d16_hi v84, v0 offset:41888
	v_sub_f32_e32 v0, v47, v93
	v_mul_f32_e32 v0, v0, v100
	v_fma_f32 v0, v0, v38, v66
	v_bfe_u32 v2, v0, 16, 1
	v_and_b32_e32 v1, 0xffff0000, v1
	v_add3_u32 v0, v0, v2, s78
	ds_write_b16_d16_hi v88, v0 offset:42976
	v_sub_f32_e32 v0, v1, v93
	v_mul_f32_e32 v0, v0, v100
	v_fmac_f32_e32 v71, v0, v43
	v_bfe_u32 v0, v71, 16, 1
	v_and_b32_e32 v3, 0xffff0000, v3
	v_add3_u32 v0, v71, v0, s78
	ds_write_b16_d16_hi v84, v0 offset:42160
	v_sub_f32_e32 v0, v3, v93
	v_and_b32_e32 v1, 0x7c, v112
	v_ashrrev_i32_e32 v38, 5, v114
	v_mul_f32_e32 v0, v0, v100
	v_cmp_le_i32_e32 vcc, v1, v38
	v_fmac_f32_e32 v67, v0, v39
	v_or_b32_e32 v36, 2, v1
	v_cndmask_b32_e32 v2, 0, v8, vcc
	v_cmp_lt_i32_e32 vcc, v1, v38
	v_bfe_u32 v0, v67, 16, 1
	v_or_b32_e32 v37, 3, v1
	v_cndmask_b32_e32 v3, 0, v9, vcc
	v_cmp_le_i32_e32 vcc, v36, v38
	v_add3_u32 v0, v67, v0, s78
	v_cvt_pk_bf16_f32 v2, v2, v3
	v_cndmask_b32_e32 v3, 0, v10, vcc
	v_cmp_le_i32_e32 vcc, v37, v38
	ds_write_b16_d16_hi v88, v0 offset:43248
	v_lshl_add_u32 v0, v1, 1, 0
	v_cndmask_b32_e32 v8, 0, v11, vcc
	v_cvt_pk_bf16_f32 v3, v3, v8
	v_mad_u64_u32 v[8:9], s[2:3], v38, s77, v[0:1]
	ds_write_b64 v8, v[2:3]
	v_ashrrev_i32_e32 v8, 5, v99
	v_cmp_le_i32_e32 vcc, v1, v8
	v_ashrrev_i32_e32 v11, 6, v114
	s_nop 0
	v_cndmask_b32_e32 v2, 0, v4, vcc
	v_cmp_lt_i32_e32 vcc, v1, v8
	s_nop 1
	v_cndmask_b32_e32 v3, 0, v5, vcc
	v_cmp_le_i32_e32 vcc, v36, v8
	v_cvt_pk_bf16_f32 v2, v2, v3
	s_nop 0
	v_cndmask_b32_e32 v3, 0, v6, vcc
	v_cmp_le_i32_e32 vcc, v37, v8
	s_nop 1
	v_cndmask_b32_e32 v4, 0, v7, vcc
	v_cvt_pk_bf16_f32 v3, v3, v4
	v_mad_u64_u32 v[4:5], s[2:3], v8, s77, v[0:1]
	ds_write_b64 v4, v[2:3]
	v_ashrrev_i32_e32 v4, 5, v98
	v_cmp_le_i32_e32 vcc, v1, v4
	s_nop 1
	v_cndmask_b32_e32 v2, 0, v12, vcc
	v_cmp_lt_i32_e32 vcc, v1, v4
	s_nop 1
	v_cndmask_b32_e32 v3, 0, v13, vcc
	v_cmp_le_i32_e32 vcc, v36, v4
	v_cvt_pk_bf16_f32 v2, v2, v3
	s_nop 0
	v_cndmask_b32_e32 v3, 0, v14, vcc
	v_cmp_le_i32_e32 vcc, v37, v4
	s_nop 1
	v_cndmask_b32_e32 v5, 0, v15, vcc
	v_cvt_pk_bf16_f32 v3, v3, v5
	v_mad_u64_u32 v[4:5], s[2:3], v4, s77, v[0:1]
	ds_write_b64 v4, v[2:3]
	v_ashrrev_i32_e32 v4, 5, v97
	v_cmp_le_i32_e32 vcc, v1, v4
	s_nop 1
	v_cndmask_b32_e32 v2, 0, v16, vcc
	v_cmp_lt_i32_e32 vcc, v1, v4
	s_nop 1
	v_cndmask_b32_e32 v3, 0, v17, vcc
	v_cmp_le_i32_e32 vcc, v36, v4
	v_cvt_pk_bf16_f32 v2, v2, v3
	s_nop 0
	v_cndmask_b32_e32 v3, 0, v18, vcc
	v_cmp_le_i32_e32 vcc, v37, v4
	s_nop 1
	v_cndmask_b32_e32 v5, 0, v19, vcc
	v_cvt_pk_bf16_f32 v3, v3, v5
	v_mad_u64_u32 v[4:5], s[2:3], v4, s77, v[0:1]
	ds_write_b64 v4, v[2:3]
	v_add_u32_e32 v2, 0x800, v114
	v_ashrrev_i32_e32 v4, 5, v2
	v_cmp_le_i32_e32 vcc, v1, v4
	s_nop 1
	v_cndmask_b32_e32 v2, 0, v20, vcc
	v_cmp_lt_i32_e32 vcc, v1, v4
	s_nop 1
	v_cndmask_b32_e32 v3, 0, v21, vcc
	v_cmp_le_i32_e32 vcc, v36, v4
	v_cvt_pk_bf16_f32 v2, v2, v3
	s_nop 0
	v_cndmask_b32_e32 v3, 0, v22, vcc
	v_cmp_le_i32_e32 vcc, v37, v4
	s_nop 1
	v_cndmask_b32_e32 v5, 0, v23, vcc
	v_cvt_pk_bf16_f32 v3, v3, v5
	v_mad_u64_u32 v[4:5], s[2:3], v4, s77, v[0:1]
	ds_write_b64 v4, v[2:3]
	v_add_u32_e32 v2, 0xa00, v114
; __device__ __forceinline__ float bf2f(bf16_t b) { return __uint_as_float(((unsigned)b) << 16); }
; __device__ __forceinline__ bf16_t f2bf(float f) { unsigned u = __float_as_uint(f); u += 0x7FFFu + ((u >> 16) & 1u); return (bf16_t)(u >> 16); }
; __device__ __forceinline__ void sg_item(const Bufs& B, int l, int s, int it, unsigned char* shm) {
;     ...
;         for (int i = 0; i < 4; ++i) { const int idx = tid + 512 * i; *(u32x4*)(uS + (idx >> 4) * 136 + (idx & 15) * 8) = uv[i]; }
;     }
;     __syncthreads();
;     const float* sb = IN(20) + (l * 4 + g) * 128;
;     for (int tile = wid; tile < 64; tile += 8) {
;         const int tm = tile >> 3, tn = tile & 7;
;         const int Kc = ((tm * 16 + 16 + 31) >> 5) << 5;
;         const f32x4 acc = mma_tile(Wm + tm * 16 * 136, 136, VnT + tn * 16 * 136, 136, Kc, lane);
;         const int c = tn * 16 + (lane & 15);
; #pragma unroll
;         for (int j = 0; j < 4; ++j) { const int tq = tm * 16 + (lane >> 4) * 4 + j;
;             B.br[2 * VEC_STRIDE + (size_t)(m0 + tq) * 512 + g * 128 + c] = f2bf(bf2f(uS[tq * 136 + c]) * (acc[j] + sb[tq])); }
	v_ashrrev_i32_e32 v4, 5, v2
	v_cmp_le_i32_e32 vcc, v1, v4
	s_nop 1
	v_cndmask_b32_e32 v2, 0, v24, vcc
	v_cmp_lt_i32_e32 vcc, v1, v4
	s_nop 1
	v_cndmask_b32_e32 v3, 0, v25, vcc
	v_cmp_le_i32_e32 vcc, v36, v4
	v_cvt_pk_bf16_f32 v2, v2, v3
	s_nop 0
	v_cndmask_b32_e32 v3, 0, v26, vcc
	v_cmp_le_i32_e32 vcc, v37, v4
	s_nop 1
	v_cndmask_b32_e32 v5, 0, v27, vcc
	v_cvt_pk_bf16_f32 v3, v3, v5
	v_mad_u64_u32 v[4:5], s[2:3], v4, s77, v[0:1]
	ds_write_b64 v4, v[2:3]
	v_add_u32_e32 v2, 0xc00, v114
	v_ashrrev_i32_e32 v4, 5, v2
	v_cmp_le_i32_e32 vcc, v1, v4
	s_nop 1
	v_cndmask_b32_e32 v2, 0, v28, vcc
	v_cmp_lt_i32_e32 vcc, v1, v4
	s_nop 1
	v_cndmask_b32_e32 v3, 0, v29, vcc
	v_cmp_le_i32_e32 vcc, v36, v4
	v_cvt_pk_bf16_f32 v2, v2, v3
	s_nop 0
	v_cndmask_b32_e32 v3, 0, v30, vcc
	v_cmp_le_i32_e32 vcc, v37, v4
	s_nop 1
	v_cndmask_b32_e32 v5, 0, v31, vcc
	v_cvt_pk_bf16_f32 v3, v3, v5
	v_mad_u64_u32 v[4:5], s[2:3], v4, s77, v[0:1]
	ds_write_b64 v4, v[2:3]
	v_add_u32_e32 v2, 0xe00, v114
	v_ashrrev_i32_e32 v4, 5, v2
	v_cmp_le_i32_e32 vcc, v1, v4
	s_nop 1
	v_cndmask_b32_e32 v2, 0, v32, vcc
	v_cmp_lt_i32_e32 vcc, v1, v4
	s_nop 1
	v_cndmask_b32_e32 v1, 0, v33, vcc
	v_cmp_le_i32_e32 vcc, v36, v4
	v_cvt_pk_bf16_f32 v2, v2, v1
	s_nop 0
	v_cndmask_b32_e32 v1, 0, v34, vcc
	v_cmp_le_i32_e32 vcc, v37, v4
	s_nop 1
	v_cndmask_b32_e32 v3, 0, v35, vcc
	v_cvt_pk_bf16_f32 v3, v1, v3
	v_mad_u64_u32 v[0:1], s[2:3], v4, s77, v[0:1]
	ds_write_b64 v0, v[2:3]
	v_add_u32_e32 v0, s39, v176
	v_mad_u64_u32 v[2:3], s[2:3], v92, s77, v[0:1]
	ds_write_b128 v2, v[48:51]
	v_mad_u64_u32 v[2:3], s[2:3], v94, s77, v[0:1]
	ds_write_b128 v2, v[52:55]
	v_mad_u64_u32 v[2:3], s[2:3], v95, s77, v[0:1]
	v_mad_u64_u32 v[0:1], s[2:3], v96, s77, v[0:1]
	ds_write_b128 v2, v[56:59]
	ds_write_b128 v0, v[60:63]
	s_waitcnt lgkmcnt(0)
	s_barrier
	s_load_dwordx2 s[2:3], s[0:1], 0xa0
	v_and_b32_e32 v108, 15, v179
	v_bfe_u32 v109, v179, 4, 2
	v_lshrrev_b32_e32 v110, 6, v179
	v_mul_u32_u24_e32 v111, 0x110, v108
	v_lshl_add_u32 v111, v109, 4, v111
	v_readfirstlane_b32 s20, v110
	s_mul_i32 s21, s20, 0x1100
	s_add_u32 s21, s21, 0x8800
	v_add_u32_e32 v112, s21, v111
	ds_read_b128 v[0:3], v112
	ds_read_b128 v[4:7], v112 offset:64
	ds_read_b128 v[8:11], v112 offset:128
	ds_read_b128 v[12:15], v112 offset:192
	s_lshl_b32 s30, s30, 9
	v_lshlrev_b32_e32 v113, 4, v109
	s_waitcnt lgkmcnt(0)
	s_add_u32 s22, s2, s30
	s_addc_u32 s23, s3, 0
	global_load_dwordx4 v[48:51], v113, s[22:23]
	global_load_dwordx4 v[52:55], v113, s[22:23] offset:64
	global_load_dwordx4 v[56:59], v113, s[22:23] offset:128
	global_load_dwordx4 v[60:63], v113, s[22:23] offset:192
	global_load_dwordx4 v[64:67], v113, s[22:23] offset:256
	global_load_dwordx4 v[68:71], v113, s[22:23] offset:320
	global_load_dwordx4 v[72:75], v113, s[22:23] offset:384
	global_load_dwordx4 v[76:79], v113, s[22:23] offset:448
	s_lshl_b32 s2, s36, 1
	s_lshl_b32 s3, s38, 10
	s_add_u32 s2, s2, s3
	s_add_u32 s2, s2, 0x2000000
	s_add_u32 s34, s40, s2
	s_addc_u32 s35, s41, 0
	v_lshl_add_u32 v114, s20, 4, v108
	v_lshlrev_b32_e32 v114, 1, v114
	v_lshl_add_u32 v115, v109, 12, v114
	v_mul_u32_u24_e32 v117, 0x440, v109
	v_add3_u32 v114, v114, v117, s39
	ds_read_b128 v[80:83], v111
	ds_read_b128 v[84:87], v111 offset:4352
	ds_read_b128 v[88:91], v111 offset:8704
	ds_read_b128 v[92:95], v111 offset:8768
	ds_read_b128 v[96:99], v111 offset:13056
	ds_read_b128 v[100:103], v111 offset:13120
	s_waitcnt lgkmcnt(0)
	v_mfma_f32_16x16x32_bf16 v[16:19], v[80:83], v[0:3], 0
	v_mfma_f32_16x16x32_bf16 v[20:23], v[84:87], v[0:3], 0
	v_mfma_f32_16x16x32_bf16 v[24:27], v[88:91], v[0:3], 0
	v_mfma_f32_16x16x32_bf16 v[24:27], v[92:95], v[4:7], v[24:27]
	v_mfma_f32_16x16x32_bf16 v[28:31], v[96:99], v[0:3], 0
	v_mfma_f32_16x16x32_bf16 v[28:31], v[100:103], v[4:7], v[28:31]
	ds_read_b128 v[80:83], v111 offset:17408
	ds_read_b128 v[84:87], v111 offset:17472
	ds_read_b128 v[88:91], v111 offset:17536
	ds_read_b128 v[92:95], v111 offset:21760
	ds_read_b128 v[96:99], v111 offset:21824
	ds_read_b128 v[100:103], v111 offset:21888
	s_waitcnt lgkmcnt(0)
	v_mfma_f32_16x16x32_bf16 v[32:35], v[80:83], v[0:3], 0
	v_mfma_f32_16x16x32_bf16 v[32:35], v[84:87], v[4:7], v[32:35]
	v_mfma_f32_16x16x32_bf16 v[32:35], v[88:91], v[8:11], v[32:35]
	v_mfma_f32_16x16x32_bf16 v[36:39], v[92:95], v[0:3], 0
	v_mfma_f32_16x16x32_bf16 v[36:39], v[96:99], v[4:7], v[36:39]
	v_mfma_f32_16x16x32_bf16 v[36:39], v[100:103], v[8:11], v[36:39]
	ds_read_b128 v[80:83], v111 offset:26112
	ds_read_b128 v[84:87], v111 offset:26176
	ds_read_b128 v[88:91], v111 offset:26240
	ds_read_b128 v[92:95], v111 offset:26304
	s_waitcnt lgkmcnt(0)
	v_mfma_f32_16x16x32_bf16 v[40:43], v[80:83], v[0:3], 0
	v_mfma_f32_16x16x32_bf16 v[40:43], v[84:87], v[4:7], v[40:43]
	v_mfma_f32_16x16x32_bf16 v[40:43], v[88:91], v[8:11], v[40:43]
	v_mfma_f32_16x16x32_bf16 v[40:43], v[92:95], v[12:15], v[40:43]
	ds_read_b128 v[80:83], v111 offset:30464
	ds_read_b128 v[84:87], v111 offset:30528
	ds_read_b128 v[88:91], v111 offset:30592
	ds_read_b128 v[92:95], v111 offset:30656
	s_waitcnt lgkmcnt(0)
	v_mfma_f32_16x16x32_bf16 v[44:47], v[80:83], v[0:3], 0
	v_mfma_f32_16x16x32_bf16 v[44:47], v[84:87], v[4:7], v[44:47]
	v_mfma_f32_16x16x32_bf16 v[44:47], v[88:91], v[8:11], v[44:47]
	v_mfma_f32_16x16x32_bf16 v[44:47], v[92:95], v[12:15], v[44:47]
	s_nop 7
	s_nop 3
	s_waitcnt vmcnt(0)
	v_mov_b32_e32 v116, v115
	ds_read_u16 v80, v114 offset:0
	ds_read_u16 v81, v114 offset:272
	ds_read_u16 v82, v114 offset:544
	ds_read_u16 v83, v114 offset:816
	s_waitcnt lgkmcnt(0)
; __device__ __forceinline__ float bf2f(bf16_t b) { return __uint_as_float(((unsigned)b) << 16); }
; __device__ __forceinline__ bf16_t f2bf(float f) { unsigned u = __float_as_uint(f); u += 0x7FFFu + ((u >> 16) & 1u); return (bf16_t)(u >> 16); }
; __device__ __forceinline__ void sg_item(const Bufs& B, int l, int s, int it, unsigned char* shm) {
;     ...
; #pragma unroll
;         for (int j = 0; j < 4; ++j) { const int tq = tm * 16 + (lane >> 4) * 4 + j;
;             B.br[2 * VEC_STRIDE + (size_t)(m0 + tq) * 512 + g * 128 + c] = f2bf(bf2f(uS[tq * 136 + c]) * (acc[j] + sb[tq])); }
;     }
	v_lshlrev_b32_e32 v80, 16, v80
	v_add_f32_e32 v84, v16, v48
	v_mul_f32_e32 v84, v84, v80
	v_bfe_u32 v88, v84, 16, 1
	v_add3_u32 v84, v84, v88, s78
	global_store_short_d16_hi v116, v84, s[34:35]
	v_lshlrev_b32_e32 v81, 16, v81
	v_add_f32_e32 v85, v17, v49
	v_mul_f32_e32 v85, v85, v81
	v_bfe_u32 v89, v85, 16, 1
	v_add3_u32 v85, v85, v89, s78
	global_store_short_d16_hi v116, v85, s[34:35] offset:1024
	v_lshlrev_b32_e32 v82, 16, v82
	v_add_f32_e32 v86, v18, v50
	v_mul_f32_e32 v86, v86, v82
	v_bfe_u32 v90, v86, 16, 1
	v_add3_u32 v86, v86, v90, s78
	global_store_short_d16_hi v116, v86, s[34:35] offset:2048
	v_lshlrev_b32_e32 v83, 16, v83
	v_add_f32_e32 v87, v19, v51
	v_mul_f32_e32 v87, v87, v83
	v_bfe_u32 v91, v87, 16, 1
	v_add3_u32 v87, v87, v91, s78
	global_store_short_d16_hi v116, v87, s[34:35] offset:3072
	v_add_u32_e32 v116, 0x4000, v115
	ds_read_u16 v80, v114 offset:4352
	ds_read_u16 v81, v114 offset:4624
	ds_read_u16 v82, v114 offset:4896
	ds_read_u16 v83, v114 offset:5168
	s_waitcnt lgkmcnt(0)
	v_lshlrev_b32_e32 v80, 16, v80
	v_add_f32_e32 v84, v20, v52
	v_mul_f32_e32 v84, v84, v80
	v_bfe_u32 v88, v84, 16, 1
	v_add3_u32 v84, v84, v88, s78
	global_store_short_d16_hi v116, v84, s[34:35]
	v_lshlrev_b32_e32 v81, 16, v81
	v_add_f32_e32 v85, v21, v53
	v_mul_f32_e32 v85, v85, v81
	v_bfe_u32 v89, v85, 16, 1
	v_add3_u32 v85, v85, v89, s78
	global_store_short_d16_hi v116, v85, s[34:35] offset:1024
	v_lshlrev_b32_e32 v82, 16, v82
	v_add_f32_e32 v86, v22, v54
	v_mul_f32_e32 v86, v86, v82
	v_bfe_u32 v90, v86, 16, 1
	v_add3_u32 v86, v86, v90, s78
	global_store_short_d16_hi v116, v86, s[34:35] offset:2048
	v_lshlrev_b32_e32 v83, 16, v83
	v_add_f32_e32 v87, v23, v55
	v_mul_f32_e32 v87, v87, v83
	v_bfe_u32 v91, v87, 16, 1
	v_add3_u32 v87, v87, v91, s78
	global_store_short_d16_hi v116, v87, s[34:35] offset:3072
	v_add_u32_e32 v116, 0x8000, v115
	ds_read_u16 v80, v114 offset:8704
	ds_read_u16 v81, v114 offset:8976
	ds_read_u16 v82, v114 offset:9248
	ds_read_u16 v83, v114 offset:9520
	s_waitcnt lgkmcnt(0)
	v_lshlrev_b32_e32 v80, 16, v80
	v_add_f32_e32 v84, v24, v56
	v_mul_f32_e32 v84, v84, v80
	v_bfe_u32 v88, v84, 16, 1
	v_add3_u32 v84, v84, v88, s78
	global_store_short_d16_hi v116, v84, s[34:35]
	v_lshlrev_b32_e32 v81, 16, v81
	v_add_f32_e32 v85, v25, v57
	v_mul_f32_e32 v85, v85, v81
	v_bfe_u32 v89, v85, 16, 1
	v_add3_u32 v85, v85, v89, s78
	global_store_short_d16_hi v116, v85, s[34:35] offset:1024
	v_lshlrev_b32_e32 v82, 16, v82
	v_add_f32_e32 v86, v26, v58
	v_mul_f32_e32 v86, v86, v82
	v_bfe_u32 v90, v86, 16, 1
	v_add3_u32 v86, v86, v90, s78
	global_store_short_d16_hi v116, v86, s[34:35] offset:2048
	v_lshlrev_b32_e32 v83, 16, v83
	v_add_f32_e32 v87, v27, v59
	v_mul_f32_e32 v87, v87, v83
	v_bfe_u32 v91, v87, 16, 1
	v_add3_u32 v87, v87, v91, s78
	global_store_short_d16_hi v116, v87, s[34:35] offset:3072
	v_add_u32_e32 v116, 0xc000, v115
	ds_read_u16 v80, v114 offset:13056
	ds_read_u16 v81, v114 offset:13328
	ds_read_u16 v82, v114 offset:13600
	ds_read_u16 v83, v114 offset:13872
	s_waitcnt lgkmcnt(0)
	v_lshlrev_b32_e32 v80, 16, v80
	v_add_f32_e32 v84, v28, v60
	v_mul_f32_e32 v84, v84, v80
	v_bfe_u32 v88, v84, 16, 1
	v_add3_u32 v84, v84, v88, s78
	global_store_short_d16_hi v116, v84, s[34:35]
	v_lshlrev_b32_e32 v81, 16, v81
	v_add_f32_e32 v85, v29, v61
	v_mul_f32_e32 v85, v85, v81
	v_bfe_u32 v89, v85, 16, 1
	v_add3_u32 v85, v85, v89, s78
	global_store_short_d16_hi v116, v85, s[34:35] offset:1024
	v_lshlrev_b32_e32 v82, 16, v82
	v_add_f32_e32 v86, v30, v62
	v_mul_f32_e32 v86, v86, v82
	v_bfe_u32 v90, v86, 16, 1
	v_add3_u32 v86, v86, v90, s78
	global_store_short_d16_hi v116, v86, s[34:35] offset:2048
	v_lshlrev_b32_e32 v83, 16, v83
	v_add_f32_e32 v87, v31, v63
	v_mul_f32_e32 v87, v87, v83
	v_bfe_u32 v91, v87, 16, 1
	v_add3_u32 v87, v87, v91, s78
	global_store_short_d16_hi v116, v87, s[34:35] offset:3072
	v_add_u32_e32 v116, 0x10000, v115
	ds_read_u16 v80, v114 offset:17408
	ds_read_u16 v81, v114 offset:17680
	ds_read_u16 v82, v114 offset:17952
	ds_read_u16 v83, v114 offset:18224
	s_waitcnt lgkmcnt(0)
; __device__ __forceinline__ float bf2f(bf16_t b) { return __uint_as_float(((unsigned)b) << 16); }
; __device__ __forceinline__ bf16_t f2bf(float f) { unsigned u = __float_as_uint(f); u += 0x7FFFu + ((u >> 16) & 1u); return (bf16_t)(u >> 16); }
; __device__ __forceinline__ void sg_item(const Bufs& B, int l, int s, int it, unsigned char* shm) {
;     ...
; #pragma unroll
;         for (int j = 0; j < 4; ++j) { const int tq = tm * 16 + (lane >> 4) * 4 + j;
;             B.br[2 * VEC_STRIDE + (size_t)(m0 + tq) * 512 + g * 128 + c] = f2bf(bf2f(uS[tq * 136 + c]) * (acc[j] + sb[tq])); }
;     }
	v_lshlrev_b32_e32 v80, 16, v80
	v_add_f32_e32 v84, v32, v64
	v_mul_f32_e32 v84, v84, v80
	v_bfe_u32 v88, v84, 16, 1
	v_add3_u32 v84, v84, v88, s78
	global_store_short_d16_hi v116, v84, s[34:35]
	v_lshlrev_b32_e32 v81, 16, v81
	v_add_f32_e32 v85, v33, v65
	v_mul_f32_e32 v85, v85, v81
	v_bfe_u32 v89, v85, 16, 1
	v_add3_u32 v85, v85, v89, s78
	global_store_short_d16_hi v116, v85, s[34:35] offset:1024
	v_lshlrev_b32_e32 v82, 16, v82
	v_add_f32_e32 v86, v34, v66
	v_mul_f32_e32 v86, v86, v82
	v_bfe_u32 v90, v86, 16, 1
	v_add3_u32 v86, v86, v90, s78
	global_store_short_d16_hi v116, v86, s[34:35] offset:2048
	v_lshlrev_b32_e32 v83, 16, v83
	v_add_f32_e32 v87, v35, v67
	v_mul_f32_e32 v87, v87, v83
	v_bfe_u32 v91, v87, 16, 1
	v_add3_u32 v87, v87, v91, s78
	global_store_short_d16_hi v116, v87, s[34:35] offset:3072
	v_add_u32_e32 v116, 0x14000, v115
	ds_read_u16 v80, v114 offset:21760
	ds_read_u16 v81, v114 offset:22032
	ds_read_u16 v82, v114 offset:22304
	ds_read_u16 v83, v114 offset:22576
	s_waitcnt lgkmcnt(0)
	v_lshlrev_b32_e32 v80, 16, v80
	v_add_f32_e32 v84, v36, v68
	v_mul_f32_e32 v84, v84, v80
	v_bfe_u32 v88, v84, 16, 1
	v_add3_u32 v84, v84, v88, s78
	global_store_short_d16_hi v116, v84, s[34:35]
	v_lshlrev_b32_e32 v81, 16, v81
	v_add_f32_e32 v85, v37, v69
	v_mul_f32_e32 v85, v85, v81
	v_bfe_u32 v89, v85, 16, 1
	v_add3_u32 v85, v85, v89, s78
	global_store_short_d16_hi v116, v85, s[34:35] offset:1024
	v_lshlrev_b32_e32 v82, 16, v82
	v_add_f32_e32 v86, v38, v70
	v_mul_f32_e32 v86, v86, v82
	v_bfe_u32 v90, v86, 16, 1
	v_add3_u32 v86, v86, v90, s78
	global_store_short_d16_hi v116, v86, s[34:35] offset:2048
	v_lshlrev_b32_e32 v83, 16, v83
	v_add_f32_e32 v87, v39, v71
	v_mul_f32_e32 v87, v87, v83
	v_bfe_u32 v91, v87, 16, 1
	v_add3_u32 v87, v87, v91, s78
	global_store_short_d16_hi v116, v87, s[34:35] offset:3072
	v_add_u32_e32 v116, 0x18000, v115
	ds_read_u16 v80, v114 offset:26112
	ds_read_u16 v81, v114 offset:26384
	ds_read_u16 v82, v114 offset:26656
	ds_read_u16 v83, v114 offset:26928
	s_waitcnt lgkmcnt(0)
	v_lshlrev_b32_e32 v80, 16, v80
	v_add_f32_e32 v84, v40, v72
	v_mul_f32_e32 v84, v84, v80
	v_bfe_u32 v88, v84, 16, 1
	v_add3_u32 v84, v84, v88, s78
	global_store_short_d16_hi v116, v84, s[34:35]
	v_lshlrev_b32_e32 v81, 16, v81
	v_add_f32_e32 v85, v41, v73
	v_mul_f32_e32 v85, v85, v81
	v_bfe_u32 v89, v85, 16, 1
	v_add3_u32 v85, v85, v89, s78
	global_store_short_d16_hi v116, v85, s[34:35] offset:1024
	v_lshlrev_b32_e32 v82, 16, v82
	v_add_f32_e32 v86, v42, v74
	v_mul_f32_e32 v86, v86, v82
	v_bfe_u32 v90, v86, 16, 1
	v_add3_u32 v86, v86, v90, s78
	global_store_short_d16_hi v116, v86, s[34:35] offset:2048
	v_lshlrev_b32_e32 v83, 16, v83
	v_add_f32_e32 v87, v43, v75
	v_mul_f32_e32 v87, v87, v83
	v_bfe_u32 v91, v87, 16, 1
	v_add3_u32 v87, v87, v91, s78
	global_store_short_d16_hi v116, v87, s[34:35] offset:3072
	v_add_u32_e32 v116, 0x1c000, v115
	ds_read_u16 v80, v114 offset:30464
	ds_read_u16 v81, v114 offset:30736
	ds_read_u16 v82, v114 offset:31008
	ds_read_u16 v83, v114 offset:31280
	s_waitcnt lgkmcnt(0)
	v_lshlrev_b32_e32 v80, 16, v80
	v_add_f32_e32 v84, v44, v76
	v_mul_f32_e32 v84, v84, v80
	v_bfe_u32 v88, v84, 16, 1
	v_add3_u32 v84, v84, v88, s78
	global_store_short_d16_hi v116, v84, s[34:35]
	v_lshlrev_b32_e32 v81, 16, v81
	v_add_f32_e32 v85, v45, v77
	v_mul_f32_e32 v85, v85, v81
	v_bfe_u32 v89, v85, 16, 1
	v_add3_u32 v85, v85, v89, s78
	global_store_short_d16_hi v116, v85, s[34:35] offset:1024
	v_lshlrev_b32_e32 v82, 16, v82
	v_add_f32_e32 v86, v46, v78
	v_mul_f32_e32 v86, v86, v82
	v_bfe_u32 v90, v86, 16, 1
	v_add3_u32 v86, v86, v90, s78
	global_store_short_d16_hi v116, v86, s[34:35] offset:2048
	v_lshlrev_b32_e32 v83, 16, v83
	v_add_f32_e32 v87, v47, v79
	v_mul_f32_e32 v87, v87, v83
	v_bfe_u32 v91, v87, 16, 1
	v_add3_u32 v87, v87, v91, s78
	global_store_short_d16_hi v116, v87, s[34:35] offset:3072
	s_mov_b64 s[20:21], exec
	s_branch .LBB0_546
